# v31 + barrier spin loops without s_sleep (s_nop 0 instead of s_sleep 1)
# baseline (speedup 1.0000x reference)
.Lmr_spin:
	global_load_dword v3, v0, s[10:11] sc1
	s_waitcnt vmcnt(0)
	v_cmp_gt_u32_e32 vcc, 0x30, v3
	s_cbranch_vccz .Lmr_ready
	s_nop 0
	s_branch .Lmr_spin

.LBB0_184:
	v_readlane_b32 s4, v254, 5
	v_readlane_b32 s5, v254, 6
	v_readlane_b32 s6, v254, 2
	s_waitcnt lgkmcnt(0)
	s_nop 2
	global_load_dword v0, v129, s[4:5] sc1
	v_readlane_b32 s4, v254, 7
	v_readlane_b32 s5, v254, 8
	s_nop 4
	global_load_dword v1, v129, s[4:5] sc1
	v_readlane_b32 s4, v254, 9
	v_readlane_b32 s5, v254, 10
	s_waitcnt vmcnt(0)
	v_add_u32_e32 v16, v1, v0
	s_nop 2
	global_load_dword v2, v129, s[4:5] sc1
	v_readlane_b32 s4, v254, 11
	v_readlane_b32 s5, v254, 12
	s_waitcnt vmcnt(0)
	v_add_u32_e32 v16, v16, v2
	s_nop 2
	global_load_dword v3, v129, s[4:5] sc1
	v_readlane_b32 s4, v254, 13
	v_readlane_b32 s5, v254, 14
	s_waitcnt vmcnt(0)
	v_add_u32_e32 v16, v16, v3
	s_nop 2
	global_load_dword v4, v129, s[4:5] sc1
	v_readlane_b32 s4, v254, 15
	v_readlane_b32 s5, v254, 16
	s_waitcnt vmcnt(0)
	v_add_u32_e32 v16, v16, v4
	s_nop 2
	global_load_dword v5, v129, s[4:5] sc1
	v_readlane_b32 s4, v254, 17
	v_readlane_b32 s5, v254, 18
	s_waitcnt vmcnt(0)
	v_add_u32_e32 v16, v16, v5
	s_nop 2
	global_load_dword v6, v129, s[4:5] sc1
	v_readlane_b32 s4, v254, 19
	v_readlane_b32 s5, v254, 20
	s_waitcnt vmcnt(0)
	v_add_u32_e32 v16, v16, v6
	s_nop 2
	global_load_dword v7, v129, s[4:5] sc1
	v_readlane_b32 s4, v254, 21
	v_readlane_b32 s5, v254, 22
	s_waitcnt vmcnt(0)
	v_add_u32_e32 v16, v16, v7
	s_nop 2
	global_load_dword v8, v129, s[4:5] sc1
	v_readlane_b32 s4, v254, 23
	v_readlane_b32 s5, v254, 24
	s_waitcnt vmcnt(0)
	v_add_u32_e32 v16, v16, v8
	s_nop 2
	global_load_dword v9, v129, s[4:5] sc1
	v_readlane_b32 s4, v254, 25
	v_readlane_b32 s5, v254, 26
	s_waitcnt vmcnt(0)
	v_add_u32_e32 v16, v16, v9
	s_nop 2
	global_load_dword v10, v129, s[4:5] sc1
	v_readlane_b32 s4, v254, 27
	v_readlane_b32 s5, v254, 28
	s_waitcnt vmcnt(0)
	v_add_u32_e32 v16, v16, v10
	s_nop 2
	global_load_dword v11, v129, s[4:5] sc1
	v_readlane_b32 s4, v254, 29
	v_readlane_b32 s5, v254, 30
	s_waitcnt vmcnt(0)
	v_add_u32_e32 v16, v16, v11
	s_nop 2
	global_load_dword v12, v129, s[4:5] sc1
	v_readlane_b32 s4, v254, 31
	v_readlane_b32 s5, v254, 32
	s_waitcnt vmcnt(0)
	v_add_u32_e32 v16, v16, v12
	s_nop 2
	global_load_dword v13, v129, s[4:5] sc1
	v_readlane_b32 s4, v254, 33
	v_readlane_b32 s5, v254, 34
	s_waitcnt vmcnt(0)
	v_add_u32_e32 v16, v16, v13
	s_nop 2
	global_load_dword v14, v129, s[4:5] sc1
	v_readlane_b32 s4, v254, 35
	v_readlane_b32 s5, v254, 36
	s_waitcnt vmcnt(0)
	v_add_u32_e32 v16, v16, v14
	s_nop 2
	global_load_dword v15, v129, s[4:5] sc1
	s_mov_b64 s[4:5], -1
	s_waitcnt vmcnt(0)
	v_add_u32_e32 v16, v16, v15
	v_cmp_eq_u32_e32 vcc, s6, v16
	s_mov_b64 s[6:7], -1
	s_cbranch_vccnz .LBB0_183
	s_and_b32 s4, s11, 0xff
	s_cmp_eq_u32 s4, 0
	s_mov_b64 s[4:5], -1
	s_mov_b64 s[8:9], -1
	s_nop 0
	s_cbranch_scc1 .LBB0_188
	s_and_b64 vcc, exec, s[8:9]
	s_cbranch_vccz .LBB0_183

.LBB0_202:
	s_and_b32 s18, s22, 0xff
	s_mov_b64 s[16:17], -1
	s_cmp_lg_u32 s18, 0
	s_mov_b64 s[20:21], -1
	s_nop 0
	s_cbranch_scc0 .LBB0_205
	s_and_b64 vcc, exec, s[20:21]
	s_cbranch_vccz .LBB0_201

.LBB0_219:
	s_and_b32 s16, s20, 0xff
	s_mov_b64 s[14:15], -1
	s_cmp_lg_u32 s16, 0
	s_mov_b64 s[18:19], -1
	s_nop 0
	s_cbranch_scc0 .LBB0_222
	s_and_b64 vcc, exec, s[18:19]
	s_cbranch_vccz .LBB0_218

.LBB0_1132:
	v_readlane_b32 s0, v254, 5
	v_readlane_b32 s1, v254, 6
	v_readlane_b32 s4, v254, 2
	s_waitcnt lgkmcnt(0)
	s_nop 2
	global_load_dword v0, v129, s[0:1] sc1
	v_readlane_b32 s0, v254, 7
	v_readlane_b32 s1, v254, 8
	s_nop 4
	global_load_dword v1, v129, s[0:1] sc1
	v_readlane_b32 s0, v254, 9
	v_readlane_b32 s1, v254, 10
	s_waitcnt vmcnt(0)
	v_add_u32_e32 v16, v1, v0
	s_nop 2
	global_load_dword v2, v129, s[0:1] sc1
	v_readlane_b32 s0, v254, 11
	v_readlane_b32 s1, v254, 12
	s_waitcnt vmcnt(0)
	v_add_u32_e32 v16, v16, v2
	s_nop 2
	global_load_dword v3, v129, s[0:1] sc1
	v_readlane_b32 s0, v254, 13
	v_readlane_b32 s1, v254, 14
	s_waitcnt vmcnt(0)
	v_add_u32_e32 v16, v16, v3
	s_nop 2
	global_load_dword v4, v129, s[0:1] sc1
	v_readlane_b32 s0, v254, 15
	v_readlane_b32 s1, v254, 16
	s_waitcnt vmcnt(0)
	v_add_u32_e32 v16, v16, v4
	s_nop 2
	global_load_dword v5, v129, s[0:1] sc1
	v_readlane_b32 s0, v254, 17
	v_readlane_b32 s1, v254, 18
	s_waitcnt vmcnt(0)
	v_add_u32_e32 v16, v16, v5
	s_nop 2
	global_load_dword v6, v129, s[0:1] sc1
	v_readlane_b32 s0, v254, 19
	v_readlane_b32 s1, v254, 20
	s_waitcnt vmcnt(0)
	v_add_u32_e32 v16, v16, v6
	s_nop 2
	global_load_dword v7, v129, s[0:1] sc1
	v_readlane_b32 s0, v254, 21
	v_readlane_b32 s1, v254, 22
	s_waitcnt vmcnt(0)
	v_add_u32_e32 v16, v16, v7
	s_nop 2
	global_load_dword v8, v129, s[0:1] sc1
	v_readlane_b32 s0, v254, 23
	v_readlane_b32 s1, v254, 24
	s_waitcnt vmcnt(0)
	v_add_u32_e32 v16, v16, v8
	s_nop 2
	global_load_dword v9, v129, s[0:1] sc1
	v_readlane_b32 s0, v254, 25
	v_readlane_b32 s1, v254, 26
	s_waitcnt vmcnt(0)
	v_add_u32_e32 v16, v16, v9
	s_nop 2
	global_load_dword v10, v129, s[0:1] sc1
	v_readlane_b32 s0, v254, 27
	v_readlane_b32 s1, v254, 28
	s_waitcnt vmcnt(0)
	v_add_u32_e32 v16, v16, v10
	s_nop 2
	global_load_dword v11, v129, s[0:1] sc1
	v_readlane_b32 s0, v254, 29
	v_readlane_b32 s1, v254, 30
	s_waitcnt vmcnt(0)
	v_add_u32_e32 v16, v16, v11
	s_nop 2
	global_load_dword v12, v129, s[0:1] sc1
	v_readlane_b32 s0, v254, 31
	v_readlane_b32 s1, v254, 32
	s_waitcnt vmcnt(0)
	v_add_u32_e32 v16, v16, v12
	s_nop 2
	global_load_dword v13, v129, s[0:1] sc1
	v_readlane_b32 s0, v254, 33
	v_readlane_b32 s1, v254, 34
	s_waitcnt vmcnt(0)
	v_add_u32_e32 v16, v16, v13
	s_nop 2
	global_load_dword v14, v129, s[0:1] sc1
	v_readlane_b32 s0, v254, 35
	v_readlane_b32 s1, v254, 36
	s_waitcnt vmcnt(0)
	v_add_u32_e32 v16, v16, v14
	s_nop 2
	global_load_dword v15, v129, s[0:1] sc1
	s_mov_b64 s[0:1], -1
	s_waitcnt vmcnt(0)
	v_add_u32_e32 v16, v16, v15
	v_cmp_eq_u32_e32 vcc, s4, v16
	s_mov_b64 s[4:5], -1
	s_cbranch_vccnz .LBB0_1131
	s_and_b32 s0, s9, 0xff
	s_cmp_eq_u32 s0, 0
	s_mov_b64 s[0:1], -1
	s_mov_b64 s[6:7], -1
	s_nop 0
	s_cbranch_scc1 .LBB0_1136
	s_and_b64 vcc, exec, s[6:7]
	s_cbranch_vccz .LBB0_1131

.LBB0_1167:
	s_and_b32 s14, s18, 0xff
	s_mov_b64 s[12:13], -1
	s_cmp_lg_u32 s14, 0
	s_mov_b64 s[16:17], -1
	s_nop 0
	s_cbranch_scc0 .LBB0_1170
	s_and_b64 vcc, exec, s[16:17]
	s_cbranch_vccz .LBB0_1166
